# FFN-in swiglu epilogue: -log2e scaling and 1+e done with packed f32 ops (24 instead of 32 VALU per row block)
# speedup vs baseline: 1.0050x; 1.0001x over previous
.LBB0_223:
	s_cmp_lt_i32 s22, 64
	s_cselect_b32 s15, s62, 0x2c00
	s_cmp_gt_i32 s22, 31
	s_cselect_b32 s15, s15, 0
	v_lshl_add_u32 v160, s22, 8, v168
	s_lshl_b32 s15, s15, 2
	s_add_u32 s15, s49, s15
	v_ashrrev_i32_e32 v161, 31, v160
	s_addc_u32 s17, s56, 0
	s_lshl_b32 s24, s64, 8
	v_lshl_add_u64 v[164:165], v[160:161], 2, s[6:7]
	s_ashr_i32 s25, s24, 31
	v_mov_b32_e32 v194, 0xbfb8aa3b
	v_mov_b32_e32 v195, 0xbfb8aa3b
	v_mov_b32_e32 v196, 1.0
	v_mov_b32_e32 v197, 1.0
	global_load_dword v161, v[164:165], off
	global_load_dword v241, v[164:165], off offset:64
	global_load_dword v242, v[164:165], off offset:128
	global_load_dword v243, v[164:165], off offset:192
	global_load_dword v244, v[164:165], off offset:512
	global_load_dword v245, v[164:165], off offset:576
	global_load_dword v246, v[164:165], off offset:640
	global_load_dword v247, v[164:165], off offset:704
	s_lshl_b64 s[24:25], s[24:25], 2
	s_add_u32 s15, s15, s24
	s_addc_u32 s17, s17, s25
	s_add_u32 s24, s15, s63
	s_addc_u32 s25, s17, 0
	global_load_dwordx4 v[112:115], v174, s[24:25]
	global_load_dwordx4 v[116:119], v174, s[24:25] offset:512
	global_load_dwordx4 v[104:107], v174, s[24:25] offset:16
	global_load_dwordx4 v[108:111], v174, s[24:25] offset:528
	v_or_b32_e32 v180, 16, v160
	v_ashrrev_i32_e32 v181, 31, v180
	v_lshl_add_u64 v[184:185], v[180:181], 2, s[6:7]
	v_lshl_or_b32 v166, s64, 7, v170
	v_mov_b64_e32 v[162:163], s[36:37]
	v_ashrrev_i32_e32 v167, 31, v166
	v_mad_i64_i32 v[178:179], s[24:25], v160, s62, v[162:163]
	v_lshlrev_b64 v[166:167], 1, v[166:167]
	v_lshl_add_u64 v[178:179], v[178:179], 0, v[166:167]
	s_andn2_b64 vcc, exec, s[2:3]
	s_mov_b64 s[2:3], -1
	s_waitcnt vmcnt(0)
	v_fmamk_f32 v161, v161, 0x3a800000, v175
	v_rsq_f32_e32 v182, v161
	s_nop 0
	v_pk_fma_f32 v[140:141], v[140:141], v[182:183], v[112:113] op_sel_hi:[1,0,1]
	v_pk_fma_f32 v[142:143], v[142:143], v[182:183], v[114:115] op_sel_hi:[1,0,1]
	v_pk_fma_f32 v[136:137], v[136:137], v[182:183], v[104:105] op_sel_hi:[1,0,1]
	v_pk_fma_f32 v[138:139], v[138:139], v[182:183], v[106:107] op_sel_hi:[1,0,1]
	v_pk_fma_f32 v[132:133], v[132:133], v[182:183], v[116:117] op_sel_hi:[1,0,1]
	v_pk_fma_f32 v[134:135], v[134:135], v[182:183], v[118:119] op_sel_hi:[1,0,1]
	v_pk_fma_f32 v[128:129], v[128:129], v[182:183], v[108:109] op_sel_hi:[1,0,1]
	v_pk_fma_f32 v[130:131], v[130:131], v[182:183], v[110:111] op_sel_hi:[1,0,1]
	v_pk_mul_f32 v[182:183], v[140:141], v[194:195]
	v_pk_mul_f32 v[186:187], v[142:143], v[194:195]
	v_pk_mul_f32 v[188:189], v[136:137], v[194:195]
	v_pk_mul_f32 v[190:191], v[138:139], v[194:195]
	v_exp_f32_e32 v182, v182
	v_exp_f32_e32 v183, v183
	v_exp_f32_e32 v186, v186
	v_exp_f32_e32 v187, v187
	v_exp_f32_e32 v188, v188
	v_exp_f32_e32 v189, v189
	v_exp_f32_e32 v190, v190
	v_exp_f32_e32 v191, v191
	v_pk_add_f32 v[182:183], v[182:183], v[196:197]
	v_pk_add_f32 v[186:187], v[186:187], v[196:197]
	v_pk_add_f32 v[188:189], v[188:189], v[196:197]
	v_pk_add_f32 v[190:191], v[190:191], v[196:197]
	v_rcp_f32_e32 v182, v182
	v_rcp_f32_e32 v183, v183
	v_rcp_f32_e32 v186, v186
	v_rcp_f32_e32 v187, v187
	v_rcp_f32_e32 v188, v188
	v_rcp_f32_e32 v189, v189
	v_rcp_f32_e32 v190, v190
	v_rcp_f32_e32 v191, v191
	v_pk_mul_f32 v[140:141], v[140:141], v[182:183]
	v_pk_mul_f32 v[142:143], v[142:143], v[186:187]
	v_pk_mul_f32 v[136:137], v[136:137], v[188:189]
	v_pk_mul_f32 v[138:139], v[138:139], v[190:191]
	v_pk_mul_f32 v[132:133], v[132:133], v[140:141]
	v_pk_mul_f32 v[134:135], v[134:135], v[142:143]
	v_pk_mul_f32 v[136:137], v[128:129], v[136:137]
	v_pk_mul_f32 v[138:139], v[130:131], v[138:139]
	v_cvt_pk_f16_f32 v128, v132, v133
	v_cvt_pk_f16_f32 v129, v134, v135
	v_cvt_pk_f16_f32 v130, v136, v137
	v_cvt_pk_f16_f32 v131, v138, v139
	global_store_dwordx4 v[178:179], v[128:131], off
	s_nop 0
	s_nop 0
	v_or_b32_e32 v128, 32, v160
	v_mad_i64_i32 v[130:131], s[24:25], v180, s62, v[162:163]
	v_lshl_add_u64 v[130:131], v[130:131], 0, v[166:167]
	v_fmamk_f32 v129, v241, 0x3a800000, v175
	v_rsq_f32_e32 v132, v129
	v_ashrrev_i32_e32 v129, 31, v128
	v_lshl_add_u64 v[134:135], v[128:129], 2, s[6:7]
	v_pk_fma_f32 v[124:125], v[124:125], v[132:133], v[112:113] op_sel_hi:[1,0,1]
	v_pk_fma_f32 v[126:127], v[126:127], v[132:133], v[114:115] op_sel_hi:[1,0,1]
	v_pk_fma_f32 v[120:121], v[120:121], v[132:133], v[104:105] op_sel_hi:[1,0,1]
	v_pk_fma_f32 v[122:123], v[122:123], v[132:133], v[106:107] op_sel_hi:[1,0,1]
	v_pk_fma_f32 v[100:101], v[100:101], v[132:133], v[116:117] op_sel_hi:[1,0,1]
	v_pk_fma_f32 v[102:103], v[102:103], v[132:133], v[118:119] op_sel_hi:[1,0,1]
	v_pk_fma_f32 v[96:97], v[96:97], v[132:133], v[108:109] op_sel_hi:[1,0,1]
	v_pk_fma_f32 v[98:99], v[98:99], v[132:133], v[110:111] op_sel_hi:[1,0,1]
	v_pk_mul_f32 v[132:133], v[124:125], v[194:195]
	v_pk_mul_f32 v[136:137], v[126:127], v[194:195]
	v_pk_mul_f32 v[138:139], v[120:121], v[194:195]
	v_pk_mul_f32 v[140:141], v[122:123], v[194:195]
	v_exp_f32_e32 v132, v132
	v_exp_f32_e32 v133, v133
	v_exp_f32_e32 v136, v136
	v_exp_f32_e32 v137, v137
	v_exp_f32_e32 v138, v138
	v_exp_f32_e32 v139, v139
	v_exp_f32_e32 v140, v140
	v_exp_f32_e32 v141, v141
	v_pk_add_f32 v[132:133], v[132:133], v[196:197]
	v_pk_add_f32 v[136:137], v[136:137], v[196:197]
	v_pk_add_f32 v[138:139], v[138:139], v[196:197]
	v_pk_add_f32 v[140:141], v[140:141], v[196:197]
	v_rcp_f32_e32 v132, v132
	v_rcp_f32_e32 v133, v133
	v_rcp_f32_e32 v136, v136
	v_rcp_f32_e32 v137, v137
	v_rcp_f32_e32 v138, v138
	v_rcp_f32_e32 v139, v139
	v_rcp_f32_e32 v140, v140
	v_rcp_f32_e32 v141, v141
	v_pk_mul_f32 v[124:125], v[124:125], v[132:133]
	v_pk_mul_f32 v[126:127], v[126:127], v[136:137]
	v_pk_mul_f32 v[120:121], v[120:121], v[138:139]
	v_pk_mul_f32 v[122:123], v[122:123], v[140:141]
	v_pk_mul_f32 v[100:101], v[100:101], v[124:125]
	v_pk_mul_f32 v[102:103], v[102:103], v[126:127]
	v_pk_mul_f32 v[120:121], v[96:97], v[120:121]
	v_pk_mul_f32 v[122:123], v[98:99], v[122:123]
	v_cvt_pk_f16_f32 v96, v100, v101
	v_cvt_pk_f16_f32 v97, v102, v103
	v_cvt_pk_f16_f32 v98, v120, v121
	v_cvt_pk_f16_f32 v99, v122, v123
	global_store_dwordx4 v[130:131], v[96:99], off
	s_nop 0
	s_nop 0
	v_or_b32_e32 v96, 48, v160
	v_mad_i64_i32 v[98:99], s[24:25], v128, s62, v[162:163]
	v_lshl_add_u64 v[98:99], v[98:99], 0, v[166:167]
	v_fmamk_f32 v97, v242, 0x3a800000, v175
	v_rsq_f32_e32 v100, v97
	v_ashrrev_i32_e32 v97, 31, v96
	v_lshl_add_u64 v[102:103], v[96:97], 2, s[6:7]
	v_pk_fma_f32 v[92:93], v[92:93], v[100:101], v[112:113] op_sel_hi:[1,0,1]
	v_pk_fma_f32 v[94:95], v[94:95], v[100:101], v[114:115] op_sel_hi:[1,0,1]
	v_pk_fma_f32 v[88:89], v[88:89], v[100:101], v[104:105] op_sel_hi:[1,0,1]
	v_pk_fma_f32 v[90:91], v[90:91], v[100:101], v[106:107] op_sel_hi:[1,0,1]
	v_pk_fma_f32 v[84:85], v[84:85], v[100:101], v[116:117] op_sel_hi:[1,0,1]
	v_pk_fma_f32 v[86:87], v[86:87], v[100:101], v[118:119] op_sel_hi:[1,0,1]
	v_pk_fma_f32 v[80:81], v[80:81], v[100:101], v[108:109] op_sel_hi:[1,0,1]
	v_pk_fma_f32 v[82:83], v[82:83], v[100:101], v[110:111] op_sel_hi:[1,0,1]
	v_pk_mul_f32 v[100:101], v[92:93], v[194:195]
	v_pk_mul_f32 v[120:121], v[94:95], v[194:195]
	v_pk_mul_f32 v[122:123], v[88:89], v[194:195]
	v_pk_mul_f32 v[124:125], v[90:91], v[194:195]
	v_exp_f32_e32 v100, v100
	v_exp_f32_e32 v101, v101
	v_exp_f32_e32 v120, v120
	v_exp_f32_e32 v121, v121
	v_exp_f32_e32 v122, v122
	v_exp_f32_e32 v123, v123
	v_exp_f32_e32 v124, v124
	v_exp_f32_e32 v125, v125
	v_pk_add_f32 v[100:101], v[100:101], v[196:197]
	v_pk_add_f32 v[120:121], v[120:121], v[196:197]
	v_pk_add_f32 v[122:123], v[122:123], v[196:197]
	v_pk_add_f32 v[124:125], v[124:125], v[196:197]
	v_rcp_f32_e32 v100, v100
	v_rcp_f32_e32 v101, v101
	v_rcp_f32_e32 v120, v120
	v_rcp_f32_e32 v121, v121
	v_rcp_f32_e32 v122, v122
	v_rcp_f32_e32 v123, v123
	v_rcp_f32_e32 v124, v124
	v_rcp_f32_e32 v125, v125
	v_pk_mul_f32 v[92:93], v[92:93], v[100:101]
	v_pk_mul_f32 v[94:95], v[94:95], v[120:121]
	v_pk_mul_f32 v[88:89], v[88:89], v[122:123]
	v_pk_mul_f32 v[90:91], v[90:91], v[124:125]
	v_pk_mul_f32 v[84:85], v[84:85], v[92:93]
	v_pk_mul_f32 v[86:87], v[86:87], v[94:95]
	v_pk_mul_f32 v[88:89], v[80:81], v[88:89]
	v_pk_mul_f32 v[90:91], v[82:83], v[90:91]
	v_cvt_pk_f16_f32 v80, v84, v85
	v_cvt_pk_f16_f32 v81, v86, v87
	v_cvt_pk_f16_f32 v82, v88, v89
	v_cvt_pk_f16_f32 v83, v90, v91
	global_store_dwordx4 v[98:99], v[80:83], off
	s_nop 0
	s_nop 0
	v_mad_i64_i32 v[82:83], s[24:25], v96, s62, v[162:163]
	v_lshl_add_u64 v[82:83], v[82:83], 0, v[166:167]
	v_fmamk_f32 v80, v243, 0x3a800000, v175
	v_rsq_f32_e32 v80, v80
	s_nop 0
	v_pk_fma_f32 v[76:77], v[76:77], v[80:81], v[112:113] op_sel_hi:[1,0,1]
	v_pk_fma_f32 v[78:79], v[78:79], v[80:81], v[114:115] op_sel_hi:[1,0,1]
	v_pk_fma_f32 v[72:73], v[72:73], v[80:81], v[104:105] op_sel_hi:[1,0,1]
	v_pk_fma_f32 v[74:75], v[74:75], v[80:81], v[106:107] op_sel_hi:[1,0,1]
	v_pk_fma_f32 v[68:69], v[68:69], v[80:81], v[116:117] op_sel_hi:[1,0,1]
	v_pk_fma_f32 v[70:71], v[70:71], v[80:81], v[118:119] op_sel_hi:[1,0,1]
	v_pk_fma_f32 v[64:65], v[64:65], v[80:81], v[108:109] op_sel_hi:[1,0,1]
	v_pk_fma_f32 v[66:67], v[66:67], v[80:81], v[110:111] op_sel_hi:[1,0,1]
	v_pk_mul_f32 v[80:81], v[76:77], v[194:195]
	v_pk_mul_f32 v[84:85], v[78:79], v[194:195]
	v_pk_mul_f32 v[86:87], v[72:73], v[194:195]
	v_pk_mul_f32 v[88:89], v[74:75], v[194:195]
	v_exp_f32_e32 v80, v80
	v_exp_f32_e32 v81, v81
	v_exp_f32_e32 v84, v84
	v_exp_f32_e32 v85, v85
	v_exp_f32_e32 v86, v86
	v_exp_f32_e32 v87, v87
	v_exp_f32_e32 v88, v88
	v_exp_f32_e32 v89, v89
	v_pk_add_f32 v[80:81], v[80:81], v[196:197]
	v_pk_add_f32 v[84:85], v[84:85], v[196:197]
	v_pk_add_f32 v[86:87], v[86:87], v[196:197]
	v_pk_add_f32 v[88:89], v[88:89], v[196:197]
	v_rcp_f32_e32 v80, v80
	v_rcp_f32_e32 v81, v81
	v_rcp_f32_e32 v84, v84
	v_rcp_f32_e32 v85, v85
	v_rcp_f32_e32 v86, v86
	v_rcp_f32_e32 v87, v87
	v_rcp_f32_e32 v88, v88
	v_rcp_f32_e32 v89, v89
	v_pk_mul_f32 v[76:77], v[76:77], v[80:81]
	v_pk_mul_f32 v[78:79], v[78:79], v[84:85]
	v_pk_mul_f32 v[72:73], v[72:73], v[86:87]
	v_pk_mul_f32 v[74:75], v[74:75], v[88:89]
	v_pk_mul_f32 v[68:69], v[68:69], v[76:77]
	v_pk_mul_f32 v[70:71], v[70:71], v[78:79]
	v_pk_mul_f32 v[72:73], v[64:65], v[72:73]
	v_pk_mul_f32 v[74:75], v[66:67], v[74:75]
	v_cvt_pk_f16_f32 v64, v68, v69
	v_cvt_pk_f16_f32 v65, v70, v71
	v_cvt_pk_f16_f32 v66, v72, v73
	v_cvt_pk_f16_f32 v67, v74, v75
	global_store_dwordx4 v[82:83], v[64:67], off
	s_nop 0
	s_nop 0
	v_add_u32_e32 v65, 0x80, v160
	v_mad_i64_i32 v[66:67], s[24:25], v65, s62, v[162:163]
	v_lshl_add_u64 v[66:67], v[66:67], 0, v[166:167]
	v_fmamk_f32 v64, v244, 0x3a800000, v175
	v_rsq_f32_e32 v64, v64
	s_nop 0
	v_pk_fma_f32 v[60:61], v[60:61], v[64:65], v[112:113] op_sel_hi:[1,0,1]
	v_pk_fma_f32 v[62:63], v[62:63], v[64:65], v[114:115] op_sel_hi:[1,0,1]
	v_pk_fma_f32 v[56:57], v[56:57], v[64:65], v[104:105] op_sel_hi:[1,0,1]
	v_pk_fma_f32 v[58:59], v[58:59], v[64:65], v[106:107] op_sel_hi:[1,0,1]
	v_pk_fma_f32 v[52:53], v[52:53], v[64:65], v[116:117] op_sel_hi:[1,0,1]
	v_pk_fma_f32 v[54:55], v[54:55], v[64:65], v[118:119] op_sel_hi:[1,0,1]
	v_pk_fma_f32 v[48:49], v[48:49], v[64:65], v[108:109] op_sel_hi:[1,0,1]
	v_pk_fma_f32 v[50:51], v[50:51], v[64:65], v[110:111] op_sel_hi:[1,0,1]
	v_pk_mul_f32 v[64:65], v[60:61], v[194:195]
	v_pk_mul_f32 v[68:69], v[62:63], v[194:195]
	v_pk_mul_f32 v[70:71], v[56:57], v[194:195]
	v_pk_mul_f32 v[72:73], v[58:59], v[194:195]
	v_exp_f32_e32 v64, v64
	v_exp_f32_e32 v65, v65
	v_exp_f32_e32 v68, v68
	v_exp_f32_e32 v69, v69
	v_exp_f32_e32 v70, v70
	v_exp_f32_e32 v71, v71
	v_exp_f32_e32 v72, v72
	v_exp_f32_e32 v73, v73
	v_pk_add_f32 v[64:65], v[64:65], v[196:197]
	v_pk_add_f32 v[68:69], v[68:69], v[196:197]
	v_pk_add_f32 v[70:71], v[70:71], v[196:197]
	v_pk_add_f32 v[72:73], v[72:73], v[196:197]
	v_rcp_f32_e32 v64, v64
	v_rcp_f32_e32 v65, v65
	v_rcp_f32_e32 v68, v68
	v_rcp_f32_e32 v69, v69
	v_rcp_f32_e32 v70, v70
	v_rcp_f32_e32 v71, v71
	v_rcp_f32_e32 v72, v72
	v_rcp_f32_e32 v73, v73
	v_pk_mul_f32 v[60:61], v[60:61], v[64:65]
	v_pk_mul_f32 v[62:63], v[62:63], v[68:69]
	v_pk_mul_f32 v[56:57], v[56:57], v[70:71]
	v_pk_mul_f32 v[58:59], v[58:59], v[72:73]
	v_pk_mul_f32 v[52:53], v[52:53], v[60:61]
	v_pk_mul_f32 v[54:55], v[54:55], v[62:63]
	v_pk_mul_f32 v[56:57], v[48:49], v[56:57]
	v_pk_mul_f32 v[58:59], v[50:51], v[58:59]
	v_cvt_pk_f16_f32 v48, v52, v53
	v_cvt_pk_f16_f32 v49, v54, v55
	v_cvt_pk_f16_f32 v50, v56, v57
	v_cvt_pk_f16_f32 v51, v58, v59
	global_store_dwordx4 v[66:67], v[48:51], off
	s_nop 0
	s_nop 0
	v_add_u32_e32 v49, 0x90, v160
	v_mad_i64_i32 v[50:51], s[24:25], v49, s62, v[162:163]
	v_lshl_add_u64 v[50:51], v[50:51], 0, v[166:167]
	v_fmamk_f32 v48, v245, 0x3a800000, v175
	v_rsq_f32_e32 v48, v48
	s_nop 0
	v_pk_fma_f32 v[44:45], v[44:45], v[48:49], v[112:113] op_sel_hi:[1,0,1]
	v_pk_fma_f32 v[46:47], v[46:47], v[48:49], v[114:115] op_sel_hi:[1,0,1]
	v_pk_fma_f32 v[40:41], v[40:41], v[48:49], v[104:105] op_sel_hi:[1,0,1]
	v_pk_fma_f32 v[42:43], v[42:43], v[48:49], v[106:107] op_sel_hi:[1,0,1]
	v_pk_fma_f32 v[36:37], v[36:37], v[48:49], v[116:117] op_sel_hi:[1,0,1]
	v_pk_fma_f32 v[38:39], v[38:39], v[48:49], v[118:119] op_sel_hi:[1,0,1]
	v_pk_fma_f32 v[32:33], v[32:33], v[48:49], v[108:109] op_sel_hi:[1,0,1]
	v_pk_fma_f32 v[34:35], v[34:35], v[48:49], v[110:111] op_sel_hi:[1,0,1]
	v_pk_mul_f32 v[48:49], v[44:45], v[194:195]
	v_pk_mul_f32 v[52:53], v[46:47], v[194:195]
	v_pk_mul_f32 v[54:55], v[40:41], v[194:195]
	v_pk_mul_f32 v[56:57], v[42:43], v[194:195]
	v_exp_f32_e32 v48, v48
	v_exp_f32_e32 v49, v49
	v_exp_f32_e32 v52, v52
	v_exp_f32_e32 v53, v53
	v_exp_f32_e32 v54, v54
	v_exp_f32_e32 v55, v55
	v_exp_f32_e32 v56, v56
	v_exp_f32_e32 v57, v57
	v_pk_add_f32 v[48:49], v[48:49], v[196:197]
	v_pk_add_f32 v[52:53], v[52:53], v[196:197]
	v_pk_add_f32 v[54:55], v[54:55], v[196:197]
	v_pk_add_f32 v[56:57], v[56:57], v[196:197]
	v_rcp_f32_e32 v48, v48
	v_rcp_f32_e32 v49, v49
	v_rcp_f32_e32 v52, v52
	v_rcp_f32_e32 v53, v53
	v_rcp_f32_e32 v54, v54
	v_rcp_f32_e32 v55, v55
	v_rcp_f32_e32 v56, v56
	v_rcp_f32_e32 v57, v57
	v_pk_mul_f32 v[44:45], v[44:45], v[48:49]
	v_pk_mul_f32 v[46:47], v[46:47], v[52:53]
	v_pk_mul_f32 v[40:41], v[40:41], v[54:55]
	v_pk_mul_f32 v[42:43], v[42:43], v[56:57]
	v_pk_mul_f32 v[36:37], v[36:37], v[44:45]
	v_pk_mul_f32 v[38:39], v[38:39], v[46:47]
	v_pk_mul_f32 v[40:41], v[32:33], v[40:41]
	v_pk_mul_f32 v[42:43], v[34:35], v[42:43]
	v_cvt_pk_f16_f32 v32, v36, v37
	v_cvt_pk_f16_f32 v33, v38, v39
	v_cvt_pk_f16_f32 v34, v40, v41
	v_cvt_pk_f16_f32 v35, v42, v43
	global_store_dwordx4 v[50:51], v[32:35], off
	s_nop 0
	s_nop 0
	v_add_u32_e32 v33, 0xa0, v160
	v_mad_i64_i32 v[34:35], s[24:25], v33, s62, v[162:163]
	v_lshl_add_u64 v[34:35], v[34:35], 0, v[166:167]
	v_fmamk_f32 v32, v246, 0x3a800000, v175
	v_rsq_f32_e32 v32, v32
	s_nop 0
	v_pk_fma_f32 v[28:29], v[28:29], v[32:33], v[112:113] op_sel_hi:[1,0,1]
	v_pk_fma_f32 v[30:31], v[30:31], v[32:33], v[114:115] op_sel_hi:[1,0,1]
	v_pk_fma_f32 v[24:25], v[24:25], v[32:33], v[104:105] op_sel_hi:[1,0,1]
	v_pk_fma_f32 v[26:27], v[26:27], v[32:33], v[106:107] op_sel_hi:[1,0,1]
	v_pk_fma_f32 v[20:21], v[20:21], v[32:33], v[116:117] op_sel_hi:[1,0,1]
	v_pk_fma_f32 v[22:23], v[22:23], v[32:33], v[118:119] op_sel_hi:[1,0,1]
	v_pk_fma_f32 v[16:17], v[16:17], v[32:33], v[108:109] op_sel_hi:[1,0,1]
	v_pk_fma_f32 v[18:19], v[18:19], v[32:33], v[110:111] op_sel_hi:[1,0,1]
	v_pk_mul_f32 v[32:33], v[28:29], v[194:195]
	v_pk_mul_f32 v[36:37], v[30:31], v[194:195]
	v_pk_mul_f32 v[38:39], v[24:25], v[194:195]
	v_pk_mul_f32 v[40:41], v[26:27], v[194:195]
	v_exp_f32_e32 v32, v32
	v_exp_f32_e32 v33, v33
	v_exp_f32_e32 v36, v36
	v_exp_f32_e32 v37, v37
	v_exp_f32_e32 v38, v38
	v_exp_f32_e32 v39, v39
	v_exp_f32_e32 v40, v40
	v_exp_f32_e32 v41, v41
	v_pk_add_f32 v[32:33], v[32:33], v[196:197]
	v_pk_add_f32 v[36:37], v[36:37], v[196:197]
	v_pk_add_f32 v[38:39], v[38:39], v[196:197]
	v_pk_add_f32 v[40:41], v[40:41], v[196:197]
	v_rcp_f32_e32 v32, v32
	v_rcp_f32_e32 v33, v33
	v_rcp_f32_e32 v36, v36
	v_rcp_f32_e32 v37, v37
	v_rcp_f32_e32 v38, v38
	v_rcp_f32_e32 v39, v39
	v_rcp_f32_e32 v40, v40
	v_rcp_f32_e32 v41, v41
	v_pk_mul_f32 v[28:29], v[28:29], v[32:33]
	v_pk_mul_f32 v[30:31], v[30:31], v[36:37]
	v_pk_mul_f32 v[24:25], v[24:25], v[38:39]
	v_pk_mul_f32 v[26:27], v[26:27], v[40:41]
	v_pk_mul_f32 v[20:21], v[20:21], v[28:29]
	v_pk_mul_f32 v[22:23], v[22:23], v[30:31]
	v_pk_mul_f32 v[24:25], v[16:17], v[24:25]
	v_pk_mul_f32 v[26:27], v[18:19], v[26:27]
	v_cvt_pk_f16_f32 v16, v20, v21
	v_cvt_pk_f16_f32 v17, v22, v23
	v_cvt_pk_f16_f32 v18, v24, v25
	v_cvt_pk_f16_f32 v19, v26, v27
	global_store_dwordx4 v[34:35], v[16:19], off
	s_nop 0
	s_nop 0
	v_add_u32_e32 v17, 0xb0, v160
	v_mad_i64_i32 v[18:19], s[24:25], v17, s62, v[162:163]
	v_lshl_add_u64 v[18:19], v[18:19], 0, v[166:167]
	v_fmamk_f32 v16, v247, 0x3a800000, v175
	v_rsq_f32_e32 v16, v16
	s_nop 0
	v_pk_fma_f32 v[12:13], v[12:13], v[16:17], v[112:113] op_sel_hi:[1,0,1]
	v_pk_fma_f32 v[14:15], v[14:15], v[16:17], v[114:115] op_sel_hi:[1,0,1]
	v_pk_fma_f32 v[8:9], v[8:9], v[16:17], v[104:105] op_sel_hi:[1,0,1]
	v_pk_fma_f32 v[10:11], v[10:11], v[16:17], v[106:107] op_sel_hi:[1,0,1]
	v_pk_fma_f32 v[4:5], v[4:5], v[16:17], v[116:117] op_sel_hi:[1,0,1]
	v_pk_fma_f32 v[6:7], v[6:7], v[16:17], v[118:119] op_sel_hi:[1,0,1]
	v_pk_fma_f32 v[0:1], v[0:1], v[16:17], v[108:109] op_sel_hi:[1,0,1]
	v_pk_fma_f32 v[2:3], v[2:3], v[16:17], v[110:111] op_sel_hi:[1,0,1]
	v_pk_mul_f32 v[16:17], v[12:13], v[194:195]
	v_pk_mul_f32 v[20:21], v[14:15], v[194:195]
	v_pk_mul_f32 v[22:23], v[8:9], v[194:195]
	v_pk_mul_f32 v[24:25], v[10:11], v[194:195]
	v_exp_f32_e32 v16, v16
	v_exp_f32_e32 v17, v17
	v_exp_f32_e32 v20, v20
	v_exp_f32_e32 v21, v21
	v_exp_f32_e32 v22, v22
	v_exp_f32_e32 v23, v23
	v_exp_f32_e32 v24, v24
	v_exp_f32_e32 v25, v25
	v_pk_add_f32 v[16:17], v[16:17], v[196:197]
	v_pk_add_f32 v[20:21], v[20:21], v[196:197]
	v_pk_add_f32 v[22:23], v[22:23], v[196:197]
	v_pk_add_f32 v[24:25], v[24:25], v[196:197]
	v_rcp_f32_e32 v16, v16
	v_rcp_f32_e32 v17, v17
	v_rcp_f32_e32 v20, v20
	v_rcp_f32_e32 v21, v21
	v_rcp_f32_e32 v22, v22
	v_rcp_f32_e32 v23, v23
	v_rcp_f32_e32 v24, v24
	v_rcp_f32_e32 v25, v25
	v_pk_mul_f32 v[12:13], v[12:13], v[16:17]
	v_pk_mul_f32 v[14:15], v[14:15], v[20:21]
	v_pk_mul_f32 v[8:9], v[8:9], v[22:23]
	v_pk_mul_f32 v[10:11], v[10:11], v[24:25]
	v_pk_mul_f32 v[4:5], v[4:5], v[12:13]
	v_pk_mul_f32 v[6:7], v[6:7], v[14:15]
	v_pk_mul_f32 v[8:9], v[0:1], v[8:9]
	v_pk_mul_f32 v[10:11], v[2:3], v[10:11]
	v_cvt_pk_f16_f32 v0, v4, v5
	v_cvt_pk_f16_f32 v1, v6, v7
	v_cvt_pk_f16_f32 v2, v8, v9
	v_cvt_pk_f16_f32 v3, v10, v11
	global_store_dwordx4 v[18:19], v[0:3], off
	s_cbranch_vccnz .LBB0_212
	s_andn2_b64 vcc, exec, s[4:5]
	s_cbranch_vccnz .LBB0_211
	s_barrier
	s_branch .LBB0_211

.LBB0_876:
	s_cmp_lt_i32 s22, 64
	s_cselect_b32 s15, s60, 0x2c00
	s_cmp_gt_i32 s22, 31
	s_cselect_b32 s15, s15, 0
	v_lshl_add_u32 v160, s22, 8, v168
	s_lshl_b32 s15, s15, 2
	s_add_u32 s15, s49, s15
	v_ashrrev_i32_e32 v161, 31, v160
	s_addc_u32 s17, s54, 0
	s_lshl_b32 s24, s62, 8
	v_lshl_add_u64 v[164:165], v[160:161], 2, s[6:7]
	s_ashr_i32 s25, s24, 31
	v_mov_b32_e32 v194, 0xbfb8aa3b
	v_mov_b32_e32 v195, 0xbfb8aa3b
	v_mov_b32_e32 v196, 1.0
	v_mov_b32_e32 v197, 1.0
	global_load_dword v161, v[164:165], off
	global_load_dword v241, v[164:165], off offset:64
	global_load_dword v242, v[164:165], off offset:128
	global_load_dword v243, v[164:165], off offset:192
	global_load_dword v244, v[164:165], off offset:512
	global_load_dword v245, v[164:165], off offset:576
	global_load_dword v246, v[164:165], off offset:640
	global_load_dword v247, v[164:165], off offset:704
	s_lshl_b64 s[24:25], s[24:25], 2
	s_add_u32 s15, s15, s24
	s_addc_u32 s17, s17, s25
	s_add_u32 s24, s15, s61
	s_addc_u32 s25, s17, 0
	global_load_dwordx4 v[112:115], v174, s[24:25]
	global_load_dwordx4 v[116:119], v174, s[24:25] offset:512
	global_load_dwordx4 v[104:107], v174, s[24:25] offset:16
	global_load_dwordx4 v[108:111], v174, s[24:25] offset:528
	v_or_b32_e32 v180, 16, v160
	v_ashrrev_i32_e32 v181, 31, v180
	v_lshl_add_u64 v[184:185], v[180:181], 2, s[6:7]
	v_lshl_or_b32 v166, s62, 7, v170
	v_mov_b64_e32 v[162:163], s[36:37]
	v_ashrrev_i32_e32 v167, 31, v166
	v_mad_i64_i32 v[178:179], s[24:25], v160, s60, v[162:163]
	v_lshlrev_b64 v[166:167], 1, v[166:167]
	v_lshl_add_u64 v[178:179], v[178:179], 0, v[166:167]
	s_andn2_b64 vcc, exec, s[2:3]
	s_mov_b64 s[2:3], -1
	s_waitcnt vmcnt(0)
	v_fmamk_f32 v161, v161, 0x3a800000, v175
	v_rsq_f32_e32 v182, v161
	s_nop 0
	v_pk_fma_f32 v[140:141], v[140:141], v[182:183], v[112:113] op_sel_hi:[1,0,1]
	v_pk_fma_f32 v[142:143], v[142:143], v[182:183], v[114:115] op_sel_hi:[1,0,1]
	v_pk_fma_f32 v[136:137], v[136:137], v[182:183], v[104:105] op_sel_hi:[1,0,1]
	v_pk_fma_f32 v[138:139], v[138:139], v[182:183], v[106:107] op_sel_hi:[1,0,1]
	v_pk_fma_f32 v[132:133], v[132:133], v[182:183], v[116:117] op_sel_hi:[1,0,1]
	v_pk_fma_f32 v[134:135], v[134:135], v[182:183], v[118:119] op_sel_hi:[1,0,1]
	v_pk_fma_f32 v[128:129], v[128:129], v[182:183], v[108:109] op_sel_hi:[1,0,1]
	v_pk_fma_f32 v[130:131], v[130:131], v[182:183], v[110:111] op_sel_hi:[1,0,1]
	v_pk_mul_f32 v[182:183], v[140:141], v[194:195]
	v_pk_mul_f32 v[186:187], v[142:143], v[194:195]
	v_pk_mul_f32 v[188:189], v[136:137], v[194:195]
	v_pk_mul_f32 v[190:191], v[138:139], v[194:195]
	v_exp_f32_e32 v182, v182
	v_exp_f32_e32 v183, v183
	v_exp_f32_e32 v186, v186
	v_exp_f32_e32 v187, v187
	v_exp_f32_e32 v188, v188
	v_exp_f32_e32 v189, v189
	v_exp_f32_e32 v190, v190
	v_exp_f32_e32 v191, v191
	v_pk_add_f32 v[182:183], v[182:183], v[196:197]
	v_pk_add_f32 v[186:187], v[186:187], v[196:197]
	v_pk_add_f32 v[188:189], v[188:189], v[196:197]
	v_pk_add_f32 v[190:191], v[190:191], v[196:197]
	v_rcp_f32_e32 v182, v182
	v_rcp_f32_e32 v183, v183
	v_rcp_f32_e32 v186, v186
	v_rcp_f32_e32 v187, v187
	v_rcp_f32_e32 v188, v188
	v_rcp_f32_e32 v189, v189
	v_rcp_f32_e32 v190, v190
	v_rcp_f32_e32 v191, v191
	v_pk_mul_f32 v[140:141], v[140:141], v[182:183]
	v_pk_mul_f32 v[142:143], v[142:143], v[186:187]
	v_pk_mul_f32 v[136:137], v[136:137], v[188:189]
	v_pk_mul_f32 v[138:139], v[138:139], v[190:191]
	v_pk_mul_f32 v[132:133], v[132:133], v[140:141]
	v_pk_mul_f32 v[134:135], v[134:135], v[142:143]
	v_pk_mul_f32 v[136:137], v[128:129], v[136:137]
	v_pk_mul_f32 v[138:139], v[130:131], v[138:139]
	v_cvt_pk_f16_f32 v128, v132, v133
	v_cvt_pk_f16_f32 v129, v134, v135
	v_cvt_pk_f16_f32 v130, v136, v137
	v_cvt_pk_f16_f32 v131, v138, v139
	global_store_dwordx4 v[178:179], v[128:131], off
	s_nop 0
	s_nop 0
	v_or_b32_e32 v128, 32, v160
	v_mad_i64_i32 v[130:131], s[24:25], v180, s60, v[162:163]
	v_lshl_add_u64 v[130:131], v[130:131], 0, v[166:167]
	v_fmamk_f32 v129, v241, 0x3a800000, v175
	v_rsq_f32_e32 v132, v129
	v_ashrrev_i32_e32 v129, 31, v128
	v_lshl_add_u64 v[134:135], v[128:129], 2, s[6:7]
	v_pk_fma_f32 v[124:125], v[124:125], v[132:133], v[112:113] op_sel_hi:[1,0,1]
	v_pk_fma_f32 v[126:127], v[126:127], v[132:133], v[114:115] op_sel_hi:[1,0,1]
	v_pk_fma_f32 v[120:121], v[120:121], v[132:133], v[104:105] op_sel_hi:[1,0,1]
	v_pk_fma_f32 v[122:123], v[122:123], v[132:133], v[106:107] op_sel_hi:[1,0,1]
	v_pk_fma_f32 v[100:101], v[100:101], v[132:133], v[116:117] op_sel_hi:[1,0,1]
	v_pk_fma_f32 v[102:103], v[102:103], v[132:133], v[118:119] op_sel_hi:[1,0,1]
	v_pk_fma_f32 v[96:97], v[96:97], v[132:133], v[108:109] op_sel_hi:[1,0,1]
	v_pk_fma_f32 v[98:99], v[98:99], v[132:133], v[110:111] op_sel_hi:[1,0,1]
	v_pk_mul_f32 v[132:133], v[124:125], v[194:195]
	v_pk_mul_f32 v[136:137], v[126:127], v[194:195]
	v_pk_mul_f32 v[138:139], v[120:121], v[194:195]
	v_pk_mul_f32 v[140:141], v[122:123], v[194:195]
	v_exp_f32_e32 v132, v132
	v_exp_f32_e32 v133, v133
	v_exp_f32_e32 v136, v136
	v_exp_f32_e32 v137, v137
	v_exp_f32_e32 v138, v138
	v_exp_f32_e32 v139, v139
	v_exp_f32_e32 v140, v140
	v_exp_f32_e32 v141, v141
	v_pk_add_f32 v[132:133], v[132:133], v[196:197]
	v_pk_add_f32 v[136:137], v[136:137], v[196:197]
	v_pk_add_f32 v[138:139], v[138:139], v[196:197]
	v_pk_add_f32 v[140:141], v[140:141], v[196:197]
	v_rcp_f32_e32 v132, v132
	v_rcp_f32_e32 v133, v133
	v_rcp_f32_e32 v136, v136
	v_rcp_f32_e32 v137, v137
	v_rcp_f32_e32 v138, v138
	v_rcp_f32_e32 v139, v139
	v_rcp_f32_e32 v140, v140
	v_rcp_f32_e32 v141, v141
	v_pk_mul_f32 v[124:125], v[124:125], v[132:133]
	v_pk_mul_f32 v[126:127], v[126:127], v[136:137]
	v_pk_mul_f32 v[120:121], v[120:121], v[138:139]
	v_pk_mul_f32 v[122:123], v[122:123], v[140:141]
	v_pk_mul_f32 v[100:101], v[100:101], v[124:125]
	v_pk_mul_f32 v[102:103], v[102:103], v[126:127]
	v_pk_mul_f32 v[120:121], v[96:97], v[120:121]
	v_pk_mul_f32 v[122:123], v[98:99], v[122:123]
	v_cvt_pk_f16_f32 v96, v100, v101
	v_cvt_pk_f16_f32 v97, v102, v103
	v_cvt_pk_f16_f32 v98, v120, v121
	v_cvt_pk_f16_f32 v99, v122, v123
	global_store_dwordx4 v[130:131], v[96:99], off
	s_nop 0
	s_nop 0
	v_or_b32_e32 v96, 48, v160
	v_mad_i64_i32 v[98:99], s[24:25], v128, s60, v[162:163]
	v_lshl_add_u64 v[98:99], v[98:99], 0, v[166:167]
	v_fmamk_f32 v97, v242, 0x3a800000, v175
	v_rsq_f32_e32 v100, v97
	v_ashrrev_i32_e32 v97, 31, v96
	v_lshl_add_u64 v[102:103], v[96:97], 2, s[6:7]
	v_pk_fma_f32 v[92:93], v[92:93], v[100:101], v[112:113] op_sel_hi:[1,0,1]
	v_pk_fma_f32 v[94:95], v[94:95], v[100:101], v[114:115] op_sel_hi:[1,0,1]
	v_pk_fma_f32 v[88:89], v[88:89], v[100:101], v[104:105] op_sel_hi:[1,0,1]
	v_pk_fma_f32 v[90:91], v[90:91], v[100:101], v[106:107] op_sel_hi:[1,0,1]
	v_pk_fma_f32 v[84:85], v[84:85], v[100:101], v[116:117] op_sel_hi:[1,0,1]
	v_pk_fma_f32 v[86:87], v[86:87], v[100:101], v[118:119] op_sel_hi:[1,0,1]
	v_pk_fma_f32 v[80:81], v[80:81], v[100:101], v[108:109] op_sel_hi:[1,0,1]
	v_pk_fma_f32 v[82:83], v[82:83], v[100:101], v[110:111] op_sel_hi:[1,0,1]
	v_pk_mul_f32 v[100:101], v[92:93], v[194:195]
	v_pk_mul_f32 v[120:121], v[94:95], v[194:195]
	v_pk_mul_f32 v[122:123], v[88:89], v[194:195]
	v_pk_mul_f32 v[124:125], v[90:91], v[194:195]
	v_exp_f32_e32 v100, v100
	v_exp_f32_e32 v101, v101
	v_exp_f32_e32 v120, v120
	v_exp_f32_e32 v121, v121
	v_exp_f32_e32 v122, v122
	v_exp_f32_e32 v123, v123
	v_exp_f32_e32 v124, v124
	v_exp_f32_e32 v125, v125
	v_pk_add_f32 v[100:101], v[100:101], v[196:197]
	v_pk_add_f32 v[120:121], v[120:121], v[196:197]
	v_pk_add_f32 v[122:123], v[122:123], v[196:197]
	v_pk_add_f32 v[124:125], v[124:125], v[196:197]
	v_rcp_f32_e32 v100, v100
	v_rcp_f32_e32 v101, v101
	v_rcp_f32_e32 v120, v120
	v_rcp_f32_e32 v121, v121
	v_rcp_f32_e32 v122, v122
	v_rcp_f32_e32 v123, v123
	v_rcp_f32_e32 v124, v124
	v_rcp_f32_e32 v125, v125
	v_pk_mul_f32 v[92:93], v[92:93], v[100:101]
	v_pk_mul_f32 v[94:95], v[94:95], v[120:121]
	v_pk_mul_f32 v[88:89], v[88:89], v[122:123]
	v_pk_mul_f32 v[90:91], v[90:91], v[124:125]
	v_pk_mul_f32 v[84:85], v[84:85], v[92:93]
	v_pk_mul_f32 v[86:87], v[86:87], v[94:95]
	v_pk_mul_f32 v[88:89], v[80:81], v[88:89]
	v_pk_mul_f32 v[90:91], v[82:83], v[90:91]
	v_cvt_pk_f16_f32 v80, v84, v85
	v_cvt_pk_f16_f32 v81, v86, v87
	v_cvt_pk_f16_f32 v82, v88, v89
	v_cvt_pk_f16_f32 v83, v90, v91
	global_store_dwordx4 v[98:99], v[80:83], off
	s_nop 0
	s_nop 0
	v_mad_i64_i32 v[82:83], s[24:25], v96, s60, v[162:163]
	v_lshl_add_u64 v[82:83], v[82:83], 0, v[166:167]
	v_fmamk_f32 v80, v243, 0x3a800000, v175
	v_rsq_f32_e32 v80, v80
	s_nop 0
	v_pk_fma_f32 v[76:77], v[76:77], v[80:81], v[112:113] op_sel_hi:[1,0,1]
	v_pk_fma_f32 v[78:79], v[78:79], v[80:81], v[114:115] op_sel_hi:[1,0,1]
	v_pk_fma_f32 v[72:73], v[72:73], v[80:81], v[104:105] op_sel_hi:[1,0,1]
	v_pk_fma_f32 v[74:75], v[74:75], v[80:81], v[106:107] op_sel_hi:[1,0,1]
	v_pk_fma_f32 v[68:69], v[68:69], v[80:81], v[116:117] op_sel_hi:[1,0,1]
	v_pk_fma_f32 v[70:71], v[70:71], v[80:81], v[118:119] op_sel_hi:[1,0,1]
	v_pk_fma_f32 v[64:65], v[64:65], v[80:81], v[108:109] op_sel_hi:[1,0,1]
	v_pk_fma_f32 v[66:67], v[66:67], v[80:81], v[110:111] op_sel_hi:[1,0,1]
	v_pk_mul_f32 v[80:81], v[76:77], v[194:195]
	v_pk_mul_f32 v[84:85], v[78:79], v[194:195]
	v_pk_mul_f32 v[86:87], v[72:73], v[194:195]
	v_pk_mul_f32 v[88:89], v[74:75], v[194:195]
	v_exp_f32_e32 v80, v80
	v_exp_f32_e32 v81, v81
	v_exp_f32_e32 v84, v84
	v_exp_f32_e32 v85, v85
	v_exp_f32_e32 v86, v86
	v_exp_f32_e32 v87, v87
	v_exp_f32_e32 v88, v88
	v_exp_f32_e32 v89, v89
	v_pk_add_f32 v[80:81], v[80:81], v[196:197]
	v_pk_add_f32 v[84:85], v[84:85], v[196:197]
	v_pk_add_f32 v[86:87], v[86:87], v[196:197]
	v_pk_add_f32 v[88:89], v[88:89], v[196:197]
	v_rcp_f32_e32 v80, v80
	v_rcp_f32_e32 v81, v81
	v_rcp_f32_e32 v84, v84
	v_rcp_f32_e32 v85, v85
	v_rcp_f32_e32 v86, v86
	v_rcp_f32_e32 v87, v87
	v_rcp_f32_e32 v88, v88
	v_rcp_f32_e32 v89, v89
	v_pk_mul_f32 v[76:77], v[76:77], v[80:81]
	v_pk_mul_f32 v[78:79], v[78:79], v[84:85]
	v_pk_mul_f32 v[72:73], v[72:73], v[86:87]
	v_pk_mul_f32 v[74:75], v[74:75], v[88:89]
	v_pk_mul_f32 v[68:69], v[68:69], v[76:77]
	v_pk_mul_f32 v[70:71], v[70:71], v[78:79]
	v_pk_mul_f32 v[72:73], v[64:65], v[72:73]
	v_pk_mul_f32 v[74:75], v[66:67], v[74:75]
	v_cvt_pk_f16_f32 v64, v68, v69
	v_cvt_pk_f16_f32 v65, v70, v71
	v_cvt_pk_f16_f32 v66, v72, v73
	v_cvt_pk_f16_f32 v67, v74, v75
	global_store_dwordx4 v[82:83], v[64:67], off
	s_nop 0
	s_nop 0
	v_add_u32_e32 v65, 0x80, v160
	v_mad_i64_i32 v[66:67], s[24:25], v65, s60, v[162:163]
	v_lshl_add_u64 v[66:67], v[66:67], 0, v[166:167]
	v_fmamk_f32 v64, v244, 0x3a800000, v175
	v_rsq_f32_e32 v64, v64
	s_nop 0
	v_pk_fma_f32 v[60:61], v[60:61], v[64:65], v[112:113] op_sel_hi:[1,0,1]
	v_pk_fma_f32 v[62:63], v[62:63], v[64:65], v[114:115] op_sel_hi:[1,0,1]
	v_pk_fma_f32 v[56:57], v[56:57], v[64:65], v[104:105] op_sel_hi:[1,0,1]
	v_pk_fma_f32 v[58:59], v[58:59], v[64:65], v[106:107] op_sel_hi:[1,0,1]
	v_pk_fma_f32 v[52:53], v[52:53], v[64:65], v[116:117] op_sel_hi:[1,0,1]
	v_pk_fma_f32 v[54:55], v[54:55], v[64:65], v[118:119] op_sel_hi:[1,0,1]
	v_pk_fma_f32 v[48:49], v[48:49], v[64:65], v[108:109] op_sel_hi:[1,0,1]
	v_pk_fma_f32 v[50:51], v[50:51], v[64:65], v[110:111] op_sel_hi:[1,0,1]
	v_pk_mul_f32 v[64:65], v[60:61], v[194:195]
	v_pk_mul_f32 v[68:69], v[62:63], v[194:195]
	v_pk_mul_f32 v[70:71], v[56:57], v[194:195]
	v_pk_mul_f32 v[72:73], v[58:59], v[194:195]
	v_exp_f32_e32 v64, v64
	v_exp_f32_e32 v65, v65
	v_exp_f32_e32 v68, v68
	v_exp_f32_e32 v69, v69
	v_exp_f32_e32 v70, v70
	v_exp_f32_e32 v71, v71
	v_exp_f32_e32 v72, v72
	v_exp_f32_e32 v73, v73
	v_pk_add_f32 v[64:65], v[64:65], v[196:197]
	v_pk_add_f32 v[68:69], v[68:69], v[196:197]
	v_pk_add_f32 v[70:71], v[70:71], v[196:197]
	v_pk_add_f32 v[72:73], v[72:73], v[196:197]
	v_rcp_f32_e32 v64, v64
	v_rcp_f32_e32 v65, v65
	v_rcp_f32_e32 v68, v68
	v_rcp_f32_e32 v69, v69
	v_rcp_f32_e32 v70, v70
	v_rcp_f32_e32 v71, v71
	v_rcp_f32_e32 v72, v72
	v_rcp_f32_e32 v73, v73
	v_pk_mul_f32 v[60:61], v[60:61], v[64:65]
	v_pk_mul_f32 v[62:63], v[62:63], v[68:69]
	v_pk_mul_f32 v[56:57], v[56:57], v[70:71]
	v_pk_mul_f32 v[58:59], v[58:59], v[72:73]
	v_pk_mul_f32 v[52:53], v[52:53], v[60:61]
	v_pk_mul_f32 v[54:55], v[54:55], v[62:63]
	v_pk_mul_f32 v[56:57], v[48:49], v[56:57]
	v_pk_mul_f32 v[58:59], v[50:51], v[58:59]
	v_cvt_pk_f16_f32 v48, v52, v53
	v_cvt_pk_f16_f32 v49, v54, v55
	v_cvt_pk_f16_f32 v50, v56, v57
	v_cvt_pk_f16_f32 v51, v58, v59
	global_store_dwordx4 v[66:67], v[48:51], off
	s_nop 0
	s_nop 0
	v_add_u32_e32 v49, 0x90, v160
	v_mad_i64_i32 v[50:51], s[24:25], v49, s60, v[162:163]
	v_lshl_add_u64 v[50:51], v[50:51], 0, v[166:167]
	v_fmamk_f32 v48, v245, 0x3a800000, v175
	v_rsq_f32_e32 v48, v48
	s_nop 0
	v_pk_fma_f32 v[44:45], v[44:45], v[48:49], v[112:113] op_sel_hi:[1,0,1]
	v_pk_fma_f32 v[46:47], v[46:47], v[48:49], v[114:115] op_sel_hi:[1,0,1]
	v_pk_fma_f32 v[40:41], v[40:41], v[48:49], v[104:105] op_sel_hi:[1,0,1]
	v_pk_fma_f32 v[42:43], v[42:43], v[48:49], v[106:107] op_sel_hi:[1,0,1]
	v_pk_fma_f32 v[36:37], v[36:37], v[48:49], v[116:117] op_sel_hi:[1,0,1]
	v_pk_fma_f32 v[38:39], v[38:39], v[48:49], v[118:119] op_sel_hi:[1,0,1]
	v_pk_fma_f32 v[32:33], v[32:33], v[48:49], v[108:109] op_sel_hi:[1,0,1]
	v_pk_fma_f32 v[34:35], v[34:35], v[48:49], v[110:111] op_sel_hi:[1,0,1]
	v_pk_mul_f32 v[48:49], v[44:45], v[194:195]
	v_pk_mul_f32 v[52:53], v[46:47], v[194:195]
	v_pk_mul_f32 v[54:55], v[40:41], v[194:195]
	v_pk_mul_f32 v[56:57], v[42:43], v[194:195]
	v_exp_f32_e32 v48, v48
	v_exp_f32_e32 v49, v49
	v_exp_f32_e32 v52, v52
	v_exp_f32_e32 v53, v53
	v_exp_f32_e32 v54, v54
	v_exp_f32_e32 v55, v55
	v_exp_f32_e32 v56, v56
	v_exp_f32_e32 v57, v57
	v_pk_add_f32 v[48:49], v[48:49], v[196:197]
	v_pk_add_f32 v[52:53], v[52:53], v[196:197]
	v_pk_add_f32 v[54:55], v[54:55], v[196:197]
	v_pk_add_f32 v[56:57], v[56:57], v[196:197]
	v_rcp_f32_e32 v48, v48
	v_rcp_f32_e32 v49, v49
	v_rcp_f32_e32 v52, v52
	v_rcp_f32_e32 v53, v53
	v_rcp_f32_e32 v54, v54
	v_rcp_f32_e32 v55, v55
	v_rcp_f32_e32 v56, v56
	v_rcp_f32_e32 v57, v57
	v_pk_mul_f32 v[44:45], v[44:45], v[48:49]
	v_pk_mul_f32 v[46:47], v[46:47], v[52:53]
	v_pk_mul_f32 v[40:41], v[40:41], v[54:55]
	v_pk_mul_f32 v[42:43], v[42:43], v[56:57]
	v_pk_mul_f32 v[36:37], v[36:37], v[44:45]
	v_pk_mul_f32 v[38:39], v[38:39], v[46:47]
	v_pk_mul_f32 v[40:41], v[32:33], v[40:41]
	v_pk_mul_f32 v[42:43], v[34:35], v[42:43]
	v_cvt_pk_f16_f32 v32, v36, v37
	v_cvt_pk_f16_f32 v33, v38, v39
	v_cvt_pk_f16_f32 v34, v40, v41
	v_cvt_pk_f16_f32 v35, v42, v43
	global_store_dwordx4 v[50:51], v[32:35], off
	s_nop 0
	s_nop 0
	v_add_u32_e32 v33, 0xa0, v160
	v_mad_i64_i32 v[34:35], s[24:25], v33, s60, v[162:163]
	v_lshl_add_u64 v[34:35], v[34:35], 0, v[166:167]
	v_fmamk_f32 v32, v246, 0x3a800000, v175
	v_rsq_f32_e32 v32, v32
	s_nop 0
	v_pk_fma_f32 v[28:29], v[28:29], v[32:33], v[112:113] op_sel_hi:[1,0,1]
	v_pk_fma_f32 v[30:31], v[30:31], v[32:33], v[114:115] op_sel_hi:[1,0,1]
	v_pk_fma_f32 v[24:25], v[24:25], v[32:33], v[104:105] op_sel_hi:[1,0,1]
	v_pk_fma_f32 v[26:27], v[26:27], v[32:33], v[106:107] op_sel_hi:[1,0,1]
	v_pk_fma_f32 v[20:21], v[20:21], v[32:33], v[116:117] op_sel_hi:[1,0,1]
	v_pk_fma_f32 v[22:23], v[22:23], v[32:33], v[118:119] op_sel_hi:[1,0,1]
	v_pk_fma_f32 v[16:17], v[16:17], v[32:33], v[108:109] op_sel_hi:[1,0,1]
	v_pk_fma_f32 v[18:19], v[18:19], v[32:33], v[110:111] op_sel_hi:[1,0,1]
	v_pk_mul_f32 v[32:33], v[28:29], v[194:195]
	v_pk_mul_f32 v[36:37], v[30:31], v[194:195]
	v_pk_mul_f32 v[38:39], v[24:25], v[194:195]
	v_pk_mul_f32 v[40:41], v[26:27], v[194:195]
	v_exp_f32_e32 v32, v32
	v_exp_f32_e32 v33, v33
	v_exp_f32_e32 v36, v36
	v_exp_f32_e32 v37, v37
	v_exp_f32_e32 v38, v38
	v_exp_f32_e32 v39, v39
	v_exp_f32_e32 v40, v40
	v_exp_f32_e32 v41, v41
	v_pk_add_f32 v[32:33], v[32:33], v[196:197]
	v_pk_add_f32 v[36:37], v[36:37], v[196:197]
	v_pk_add_f32 v[38:39], v[38:39], v[196:197]
	v_pk_add_f32 v[40:41], v[40:41], v[196:197]
	v_rcp_f32_e32 v32, v32
	v_rcp_f32_e32 v33, v33
	v_rcp_f32_e32 v36, v36
	v_rcp_f32_e32 v37, v37
	v_rcp_f32_e32 v38, v38
	v_rcp_f32_e32 v39, v39
	v_rcp_f32_e32 v40, v40
	v_rcp_f32_e32 v41, v41
	v_pk_mul_f32 v[28:29], v[28:29], v[32:33]
	v_pk_mul_f32 v[30:31], v[30:31], v[36:37]
	v_pk_mul_f32 v[24:25], v[24:25], v[38:39]
	v_pk_mul_f32 v[26:27], v[26:27], v[40:41]
	v_pk_mul_f32 v[20:21], v[20:21], v[28:29]
	v_pk_mul_f32 v[22:23], v[22:23], v[30:31]
	v_pk_mul_f32 v[24:25], v[16:17], v[24:25]
	v_pk_mul_f32 v[26:27], v[18:19], v[26:27]
	v_cvt_pk_f16_f32 v16, v20, v21
	v_cvt_pk_f16_f32 v17, v22, v23
	v_cvt_pk_f16_f32 v18, v24, v25
	v_cvt_pk_f16_f32 v19, v26, v27
	global_store_dwordx4 v[34:35], v[16:19], off
	s_nop 0
	s_nop 0
	v_add_u32_e32 v17, 0xb0, v160
	v_mad_i64_i32 v[18:19], s[24:25], v17, s60, v[162:163]
	v_lshl_add_u64 v[18:19], v[18:19], 0, v[166:167]
	v_fmamk_f32 v16, v247, 0x3a800000, v175
	v_rsq_f32_e32 v16, v16
	s_nop 0
	v_pk_fma_f32 v[12:13], v[12:13], v[16:17], v[112:113] op_sel_hi:[1,0,1]
	v_pk_fma_f32 v[14:15], v[14:15], v[16:17], v[114:115] op_sel_hi:[1,0,1]
	v_pk_fma_f32 v[8:9], v[8:9], v[16:17], v[104:105] op_sel_hi:[1,0,1]
	v_pk_fma_f32 v[10:11], v[10:11], v[16:17], v[106:107] op_sel_hi:[1,0,1]
	v_pk_fma_f32 v[4:5], v[4:5], v[16:17], v[116:117] op_sel_hi:[1,0,1]
	v_pk_fma_f32 v[6:7], v[6:7], v[16:17], v[118:119] op_sel_hi:[1,0,1]
	v_pk_fma_f32 v[0:1], v[0:1], v[16:17], v[108:109] op_sel_hi:[1,0,1]
	v_pk_fma_f32 v[2:3], v[2:3], v[16:17], v[110:111] op_sel_hi:[1,0,1]
	v_pk_mul_f32 v[16:17], v[12:13], v[194:195]
	v_pk_mul_f32 v[20:21], v[14:15], v[194:195]
	v_pk_mul_f32 v[22:23], v[8:9], v[194:195]
	v_pk_mul_f32 v[24:25], v[10:11], v[194:195]
	v_exp_f32_e32 v16, v16
	v_exp_f32_e32 v17, v17
	v_exp_f32_e32 v20, v20
	v_exp_f32_e32 v21, v21
	v_exp_f32_e32 v22, v22
	v_exp_f32_e32 v23, v23
	v_exp_f32_e32 v24, v24
	v_exp_f32_e32 v25, v25
	v_pk_add_f32 v[16:17], v[16:17], v[196:197]
	v_pk_add_f32 v[20:21], v[20:21], v[196:197]
	v_pk_add_f32 v[22:23], v[22:23], v[196:197]
	v_pk_add_f32 v[24:25], v[24:25], v[196:197]
	v_rcp_f32_e32 v16, v16
	v_rcp_f32_e32 v17, v17
	v_rcp_f32_e32 v20, v20
	v_rcp_f32_e32 v21, v21
	v_rcp_f32_e32 v22, v22
	v_rcp_f32_e32 v23, v23
	v_rcp_f32_e32 v24, v24
	v_rcp_f32_e32 v25, v25
	v_pk_mul_f32 v[12:13], v[12:13], v[16:17]
	v_pk_mul_f32 v[14:15], v[14:15], v[20:21]
	v_pk_mul_f32 v[8:9], v[8:9], v[22:23]
	v_pk_mul_f32 v[10:11], v[10:11], v[24:25]
	v_pk_mul_f32 v[4:5], v[4:5], v[12:13]
	v_pk_mul_f32 v[6:7], v[6:7], v[14:15]
	v_pk_mul_f32 v[8:9], v[0:1], v[8:9]
	v_pk_mul_f32 v[10:11], v[2:3], v[10:11]
	v_cvt_pk_f16_f32 v0, v4, v5
	v_cvt_pk_f16_f32 v1, v6, v7
	v_cvt_pk_f16_f32 v2, v8, v9
	v_cvt_pk_f16_f32 v3, v10, v11
	global_store_dwordx4 v[18:19], v[0:3], off
	s_cbranch_vccnz .LBB0_865
	s_andn2_b64 vcc, exec, s[4:5]
	s_cbranch_vccnz .LBB0_864
	s_barrier
	s_branch .LBB0_864

.LBB0_1588:
	s_cmp_lt_i32 s22, 64
	s_cselect_b32 s15, s57, 0x2c00
	s_cmp_gt_i32 s22, 31
	s_cselect_b32 s15, s15, 0
	v_lshl_add_u32 v160, s22, 8, v168
	s_lshl_b32 s15, s15, 2
	s_add_u32 s15, s50, s15
	v_ashrrev_i32_e32 v161, 31, v160
	s_addc_u32 s17, s51, 0
	s_lshl_b32 s24, s59, 8
	v_lshl_add_u64 v[164:165], v[160:161], 2, s[6:7]
	s_ashr_i32 s25, s24, 31
	v_mov_b32_e32 v194, 0xbfb8aa3b
	v_mov_b32_e32 v195, 0xbfb8aa3b
	v_mov_b32_e32 v196, 1.0
	v_mov_b32_e32 v197, 1.0
	global_load_dword v161, v[164:165], off
	global_load_dword v241, v[164:165], off offset:64
	global_load_dword v242, v[164:165], off offset:128
	global_load_dword v243, v[164:165], off offset:192
	global_load_dword v244, v[164:165], off offset:512
	global_load_dword v245, v[164:165], off offset:576
	global_load_dword v246, v[164:165], off offset:640
	global_load_dword v247, v[164:165], off offset:704
	s_lshl_b64 s[24:25], s[24:25], 2
	s_add_u32 s15, s15, s24
	s_addc_u32 s17, s17, s25
	s_add_u32 s24, s15, s58
	s_addc_u32 s25, s17, 0
	global_load_dwordx4 v[112:115], v174, s[24:25]
	global_load_dwordx4 v[116:119], v174, s[24:25] offset:512
	global_load_dwordx4 v[104:107], v174, s[24:25] offset:16
	global_load_dwordx4 v[108:111], v174, s[24:25] offset:528
	v_or_b32_e32 v180, 16, v160
	v_ashrrev_i32_e32 v181, 31, v180
	v_lshl_add_u64 v[184:185], v[180:181], 2, s[6:7]
	v_lshl_or_b32 v166, s59, 7, v170
	v_mov_b64_e32 v[162:163], s[36:37]
	v_ashrrev_i32_e32 v167, 31, v166
	v_mad_i64_i32 v[178:179], s[24:25], v160, s57, v[162:163]
	v_lshlrev_b64 v[166:167], 1, v[166:167]
	v_lshl_add_u64 v[178:179], v[178:179], 0, v[166:167]
	s_andn2_b64 vcc, exec, s[2:3]
	s_mov_b64 s[2:3], -1
	s_waitcnt vmcnt(0)
	v_fmamk_f32 v161, v161, 0x3a800000, v175
	v_rsq_f32_e32 v182, v161
	s_nop 0
	v_pk_fma_f32 v[140:141], v[140:141], v[182:183], v[112:113] op_sel_hi:[1,0,1]
	v_pk_fma_f32 v[142:143], v[142:143], v[182:183], v[114:115] op_sel_hi:[1,0,1]
	v_pk_fma_f32 v[136:137], v[136:137], v[182:183], v[104:105] op_sel_hi:[1,0,1]
	v_pk_fma_f32 v[138:139], v[138:139], v[182:183], v[106:107] op_sel_hi:[1,0,1]
	v_pk_fma_f32 v[132:133], v[132:133], v[182:183], v[116:117] op_sel_hi:[1,0,1]
	v_pk_fma_f32 v[134:135], v[134:135], v[182:183], v[118:119] op_sel_hi:[1,0,1]
	v_pk_fma_f32 v[128:129], v[128:129], v[182:183], v[108:109] op_sel_hi:[1,0,1]
	v_pk_fma_f32 v[130:131], v[130:131], v[182:183], v[110:111] op_sel_hi:[1,0,1]
	v_pk_mul_f32 v[182:183], v[140:141], v[194:195]
	v_pk_mul_f32 v[186:187], v[142:143], v[194:195]
	v_pk_mul_f32 v[188:189], v[136:137], v[194:195]
	v_pk_mul_f32 v[190:191], v[138:139], v[194:195]
	v_exp_f32_e32 v182, v182
	v_exp_f32_e32 v183, v183
	v_exp_f32_e32 v186, v186
	v_exp_f32_e32 v187, v187
	v_exp_f32_e32 v188, v188
	v_exp_f32_e32 v189, v189
	v_exp_f32_e32 v190, v190
	v_exp_f32_e32 v191, v191
	v_pk_add_f32 v[182:183], v[182:183], v[196:197]
	v_pk_add_f32 v[186:187], v[186:187], v[196:197]
	v_pk_add_f32 v[188:189], v[188:189], v[196:197]
	v_pk_add_f32 v[190:191], v[190:191], v[196:197]
	v_rcp_f32_e32 v182, v182
	v_rcp_f32_e32 v183, v183
	v_rcp_f32_e32 v186, v186
	v_rcp_f32_e32 v187, v187
	v_rcp_f32_e32 v188, v188
	v_rcp_f32_e32 v189, v189
	v_rcp_f32_e32 v190, v190
	v_rcp_f32_e32 v191, v191
	v_pk_mul_f32 v[140:141], v[140:141], v[182:183]
	v_pk_mul_f32 v[142:143], v[142:143], v[186:187]
	v_pk_mul_f32 v[136:137], v[136:137], v[188:189]
	v_pk_mul_f32 v[138:139], v[138:139], v[190:191]
	v_pk_mul_f32 v[132:133], v[132:133], v[140:141]
	v_pk_mul_f32 v[134:135], v[134:135], v[142:143]
	v_pk_mul_f32 v[136:137], v[128:129], v[136:137]
	v_pk_mul_f32 v[138:139], v[130:131], v[138:139]
	v_cvt_pk_f16_f32 v128, v132, v133
	v_cvt_pk_f16_f32 v129, v134, v135
	v_cvt_pk_f16_f32 v130, v136, v137
	v_cvt_pk_f16_f32 v131, v138, v139
	global_store_dwordx4 v[178:179], v[128:131], off
	s_nop 0
	s_nop 0
	v_or_b32_e32 v128, 32, v160
	v_mad_i64_i32 v[130:131], s[24:25], v180, s57, v[162:163]
	v_lshl_add_u64 v[130:131], v[130:131], 0, v[166:167]
	v_fmamk_f32 v129, v241, 0x3a800000, v175
	v_rsq_f32_e32 v132, v129
	v_ashrrev_i32_e32 v129, 31, v128
	v_lshl_add_u64 v[134:135], v[128:129], 2, s[6:7]
	v_pk_fma_f32 v[124:125], v[124:125], v[132:133], v[112:113] op_sel_hi:[1,0,1]
	v_pk_fma_f32 v[126:127], v[126:127], v[132:133], v[114:115] op_sel_hi:[1,0,1]
	v_pk_fma_f32 v[120:121], v[120:121], v[132:133], v[104:105] op_sel_hi:[1,0,1]
	v_pk_fma_f32 v[122:123], v[122:123], v[132:133], v[106:107] op_sel_hi:[1,0,1]
	v_pk_fma_f32 v[100:101], v[100:101], v[132:133], v[116:117] op_sel_hi:[1,0,1]
	v_pk_fma_f32 v[102:103], v[102:103], v[132:133], v[118:119] op_sel_hi:[1,0,1]
	v_pk_fma_f32 v[96:97], v[96:97], v[132:133], v[108:109] op_sel_hi:[1,0,1]
	v_pk_fma_f32 v[98:99], v[98:99], v[132:133], v[110:111] op_sel_hi:[1,0,1]
	v_pk_mul_f32 v[132:133], v[124:125], v[194:195]
	v_pk_mul_f32 v[136:137], v[126:127], v[194:195]
	v_pk_mul_f32 v[138:139], v[120:121], v[194:195]
	v_pk_mul_f32 v[140:141], v[122:123], v[194:195]
	v_exp_f32_e32 v132, v132
	v_exp_f32_e32 v133, v133
	v_exp_f32_e32 v136, v136
	v_exp_f32_e32 v137, v137
	v_exp_f32_e32 v138, v138
	v_exp_f32_e32 v139, v139
	v_exp_f32_e32 v140, v140
	v_exp_f32_e32 v141, v141
	v_pk_add_f32 v[132:133], v[132:133], v[196:197]
	v_pk_add_f32 v[136:137], v[136:137], v[196:197]
	v_pk_add_f32 v[138:139], v[138:139], v[196:197]
	v_pk_add_f32 v[140:141], v[140:141], v[196:197]
	v_rcp_f32_e32 v132, v132
	v_rcp_f32_e32 v133, v133
	v_rcp_f32_e32 v136, v136
	v_rcp_f32_e32 v137, v137
	v_rcp_f32_e32 v138, v138
	v_rcp_f32_e32 v139, v139
	v_rcp_f32_e32 v140, v140
	v_rcp_f32_e32 v141, v141
	v_pk_mul_f32 v[124:125], v[124:125], v[132:133]
	v_pk_mul_f32 v[126:127], v[126:127], v[136:137]
	v_pk_mul_f32 v[120:121], v[120:121], v[138:139]
	v_pk_mul_f32 v[122:123], v[122:123], v[140:141]
	v_pk_mul_f32 v[100:101], v[100:101], v[124:125]
	v_pk_mul_f32 v[102:103], v[102:103], v[126:127]
	v_pk_mul_f32 v[120:121], v[96:97], v[120:121]
	v_pk_mul_f32 v[122:123], v[98:99], v[122:123]
	v_cvt_pk_f16_f32 v96, v100, v101
	v_cvt_pk_f16_f32 v97, v102, v103
	v_cvt_pk_f16_f32 v98, v120, v121
	v_cvt_pk_f16_f32 v99, v122, v123
	global_store_dwordx4 v[130:131], v[96:99], off
	s_nop 0
	s_nop 0
	v_or_b32_e32 v96, 48, v160
	v_mad_i64_i32 v[98:99], s[24:25], v128, s57, v[162:163]
	v_lshl_add_u64 v[98:99], v[98:99], 0, v[166:167]
	v_fmamk_f32 v97, v242, 0x3a800000, v175
	v_rsq_f32_e32 v100, v97
	v_ashrrev_i32_e32 v97, 31, v96
	v_lshl_add_u64 v[102:103], v[96:97], 2, s[6:7]
	v_pk_fma_f32 v[92:93], v[92:93], v[100:101], v[112:113] op_sel_hi:[1,0,1]
	v_pk_fma_f32 v[94:95], v[94:95], v[100:101], v[114:115] op_sel_hi:[1,0,1]
	v_pk_fma_f32 v[88:89], v[88:89], v[100:101], v[104:105] op_sel_hi:[1,0,1]
	v_pk_fma_f32 v[90:91], v[90:91], v[100:101], v[106:107] op_sel_hi:[1,0,1]
	v_pk_fma_f32 v[84:85], v[84:85], v[100:101], v[116:117] op_sel_hi:[1,0,1]
	v_pk_fma_f32 v[86:87], v[86:87], v[100:101], v[118:119] op_sel_hi:[1,0,1]
	v_pk_fma_f32 v[80:81], v[80:81], v[100:101], v[108:109] op_sel_hi:[1,0,1]
	v_pk_fma_f32 v[82:83], v[82:83], v[100:101], v[110:111] op_sel_hi:[1,0,1]
	v_pk_mul_f32 v[100:101], v[92:93], v[194:195]
	v_pk_mul_f32 v[120:121], v[94:95], v[194:195]
	v_pk_mul_f32 v[122:123], v[88:89], v[194:195]
	v_pk_mul_f32 v[124:125], v[90:91], v[194:195]
	v_exp_f32_e32 v100, v100
	v_exp_f32_e32 v101, v101
	v_exp_f32_e32 v120, v120
	v_exp_f32_e32 v121, v121
	v_exp_f32_e32 v122, v122
	v_exp_f32_e32 v123, v123
	v_exp_f32_e32 v124, v124
	v_exp_f32_e32 v125, v125
	v_pk_add_f32 v[100:101], v[100:101], v[196:197]
	v_pk_add_f32 v[120:121], v[120:121], v[196:197]
	v_pk_add_f32 v[122:123], v[122:123], v[196:197]
	v_pk_add_f32 v[124:125], v[124:125], v[196:197]
	v_rcp_f32_e32 v100, v100
	v_rcp_f32_e32 v101, v101
	v_rcp_f32_e32 v120, v120
	v_rcp_f32_e32 v121, v121
	v_rcp_f32_e32 v122, v122
	v_rcp_f32_e32 v123, v123
	v_rcp_f32_e32 v124, v124
	v_rcp_f32_e32 v125, v125
	v_pk_mul_f32 v[92:93], v[92:93], v[100:101]
	v_pk_mul_f32 v[94:95], v[94:95], v[120:121]
	v_pk_mul_f32 v[88:89], v[88:89], v[122:123]
	v_pk_mul_f32 v[90:91], v[90:91], v[124:125]
	v_pk_mul_f32 v[84:85], v[84:85], v[92:93]
	v_pk_mul_f32 v[86:87], v[86:87], v[94:95]
	v_pk_mul_f32 v[88:89], v[80:81], v[88:89]
	v_pk_mul_f32 v[90:91], v[82:83], v[90:91]
	v_cvt_pk_f16_f32 v80, v84, v85
	v_cvt_pk_f16_f32 v81, v86, v87
	v_cvt_pk_f16_f32 v82, v88, v89
	v_cvt_pk_f16_f32 v83, v90, v91
	global_store_dwordx4 v[98:99], v[80:83], off
	s_nop 0
	s_nop 0
	v_mad_i64_i32 v[82:83], s[24:25], v96, s57, v[162:163]
	v_lshl_add_u64 v[82:83], v[82:83], 0, v[166:167]
	v_fmamk_f32 v80, v243, 0x3a800000, v175
	v_rsq_f32_e32 v80, v80
	s_nop 0
	v_pk_fma_f32 v[76:77], v[76:77], v[80:81], v[112:113] op_sel_hi:[1,0,1]
	v_pk_fma_f32 v[78:79], v[78:79], v[80:81], v[114:115] op_sel_hi:[1,0,1]
	v_pk_fma_f32 v[72:73], v[72:73], v[80:81], v[104:105] op_sel_hi:[1,0,1]
	v_pk_fma_f32 v[74:75], v[74:75], v[80:81], v[106:107] op_sel_hi:[1,0,1]
	v_pk_fma_f32 v[68:69], v[68:69], v[80:81], v[116:117] op_sel_hi:[1,0,1]
	v_pk_fma_f32 v[70:71], v[70:71], v[80:81], v[118:119] op_sel_hi:[1,0,1]
	v_pk_fma_f32 v[64:65], v[64:65], v[80:81], v[108:109] op_sel_hi:[1,0,1]
	v_pk_fma_f32 v[66:67], v[66:67], v[80:81], v[110:111] op_sel_hi:[1,0,1]
	v_pk_mul_f32 v[80:81], v[76:77], v[194:195]
	v_pk_mul_f32 v[84:85], v[78:79], v[194:195]
	v_pk_mul_f32 v[86:87], v[72:73], v[194:195]
	v_pk_mul_f32 v[88:89], v[74:75], v[194:195]
	v_exp_f32_e32 v80, v80
	v_exp_f32_e32 v81, v81
	v_exp_f32_e32 v84, v84
	v_exp_f32_e32 v85, v85
	v_exp_f32_e32 v86, v86
	v_exp_f32_e32 v87, v87
	v_exp_f32_e32 v88, v88
	v_exp_f32_e32 v89, v89
	v_pk_add_f32 v[80:81], v[80:81], v[196:197]
	v_pk_add_f32 v[84:85], v[84:85], v[196:197]
	v_pk_add_f32 v[86:87], v[86:87], v[196:197]
	v_pk_add_f32 v[88:89], v[88:89], v[196:197]
	v_rcp_f32_e32 v80, v80
	v_rcp_f32_e32 v81, v81
	v_rcp_f32_e32 v84, v84
	v_rcp_f32_e32 v85, v85
	v_rcp_f32_e32 v86, v86
	v_rcp_f32_e32 v87, v87
	v_rcp_f32_e32 v88, v88
	v_rcp_f32_e32 v89, v89
	v_pk_mul_f32 v[76:77], v[76:77], v[80:81]
	v_pk_mul_f32 v[78:79], v[78:79], v[84:85]
	v_pk_mul_f32 v[72:73], v[72:73], v[86:87]
	v_pk_mul_f32 v[74:75], v[74:75], v[88:89]
	v_pk_mul_f32 v[68:69], v[68:69], v[76:77]
	v_pk_mul_f32 v[70:71], v[70:71], v[78:79]
	v_pk_mul_f32 v[72:73], v[64:65], v[72:73]
	v_pk_mul_f32 v[74:75], v[66:67], v[74:75]
	v_cvt_pk_f16_f32 v64, v68, v69
	v_cvt_pk_f16_f32 v65, v70, v71
	v_cvt_pk_f16_f32 v66, v72, v73
	v_cvt_pk_f16_f32 v67, v74, v75
	global_store_dwordx4 v[82:83], v[64:67], off
	s_nop 0
	s_nop 0
	v_add_u32_e32 v65, 0x80, v160
	v_mad_i64_i32 v[66:67], s[24:25], v65, s57, v[162:163]
	v_lshl_add_u64 v[66:67], v[66:67], 0, v[166:167]
	v_fmamk_f32 v64, v244, 0x3a800000, v175
	v_rsq_f32_e32 v64, v64
	s_nop 0
	v_pk_fma_f32 v[60:61], v[60:61], v[64:65], v[112:113] op_sel_hi:[1,0,1]
	v_pk_fma_f32 v[62:63], v[62:63], v[64:65], v[114:115] op_sel_hi:[1,0,1]
	v_pk_fma_f32 v[56:57], v[56:57], v[64:65], v[104:105] op_sel_hi:[1,0,1]
	v_pk_fma_f32 v[58:59], v[58:59], v[64:65], v[106:107] op_sel_hi:[1,0,1]
	v_pk_fma_f32 v[52:53], v[52:53], v[64:65], v[116:117] op_sel_hi:[1,0,1]
	v_pk_fma_f32 v[54:55], v[54:55], v[64:65], v[118:119] op_sel_hi:[1,0,1]
	v_pk_fma_f32 v[48:49], v[48:49], v[64:65], v[108:109] op_sel_hi:[1,0,1]
	v_pk_fma_f32 v[50:51], v[50:51], v[64:65], v[110:111] op_sel_hi:[1,0,1]
	v_pk_mul_f32 v[64:65], v[60:61], v[194:195]
	v_pk_mul_f32 v[68:69], v[62:63], v[194:195]
	v_pk_mul_f32 v[70:71], v[56:57], v[194:195]
	v_pk_mul_f32 v[72:73], v[58:59], v[194:195]
	v_exp_f32_e32 v64, v64
	v_exp_f32_e32 v65, v65
	v_exp_f32_e32 v68, v68
	v_exp_f32_e32 v69, v69
	v_exp_f32_e32 v70, v70
	v_exp_f32_e32 v71, v71
	v_exp_f32_e32 v72, v72
	v_exp_f32_e32 v73, v73
	v_pk_add_f32 v[64:65], v[64:65], v[196:197]
	v_pk_add_f32 v[68:69], v[68:69], v[196:197]
	v_pk_add_f32 v[70:71], v[70:71], v[196:197]
	v_pk_add_f32 v[72:73], v[72:73], v[196:197]
	v_rcp_f32_e32 v64, v64
	v_rcp_f32_e32 v65, v65
	v_rcp_f32_e32 v68, v68
	v_rcp_f32_e32 v69, v69
	v_rcp_f32_e32 v70, v70
	v_rcp_f32_e32 v71, v71
	v_rcp_f32_e32 v72, v72
	v_rcp_f32_e32 v73, v73
	v_pk_mul_f32 v[60:61], v[60:61], v[64:65]
	v_pk_mul_f32 v[62:63], v[62:63], v[68:69]
	v_pk_mul_f32 v[56:57], v[56:57], v[70:71]
	v_pk_mul_f32 v[58:59], v[58:59], v[72:73]
	v_pk_mul_f32 v[52:53], v[52:53], v[60:61]
	v_pk_mul_f32 v[54:55], v[54:55], v[62:63]
	v_pk_mul_f32 v[56:57], v[48:49], v[56:57]
	v_pk_mul_f32 v[58:59], v[50:51], v[58:59]
	v_cvt_pk_f16_f32 v48, v52, v53
	v_cvt_pk_f16_f32 v49, v54, v55
	v_cvt_pk_f16_f32 v50, v56, v57
	v_cvt_pk_f16_f32 v51, v58, v59
	global_store_dwordx4 v[66:67], v[48:51], off
	s_nop 0
	s_nop 0
	v_add_u32_e32 v49, 0x90, v160
	v_mad_i64_i32 v[50:51], s[24:25], v49, s57, v[162:163]
	v_lshl_add_u64 v[50:51], v[50:51], 0, v[166:167]
	v_fmamk_f32 v48, v245, 0x3a800000, v175
	v_rsq_f32_e32 v48, v48
	s_nop 0
	v_pk_fma_f32 v[44:45], v[44:45], v[48:49], v[112:113] op_sel_hi:[1,0,1]
	v_pk_fma_f32 v[46:47], v[46:47], v[48:49], v[114:115] op_sel_hi:[1,0,1]
	v_pk_fma_f32 v[40:41], v[40:41], v[48:49], v[104:105] op_sel_hi:[1,0,1]
	v_pk_fma_f32 v[42:43], v[42:43], v[48:49], v[106:107] op_sel_hi:[1,0,1]
	v_pk_fma_f32 v[36:37], v[36:37], v[48:49], v[116:117] op_sel_hi:[1,0,1]
	v_pk_fma_f32 v[38:39], v[38:39], v[48:49], v[118:119] op_sel_hi:[1,0,1]
	v_pk_fma_f32 v[32:33], v[32:33], v[48:49], v[108:109] op_sel_hi:[1,0,1]
	v_pk_fma_f32 v[34:35], v[34:35], v[48:49], v[110:111] op_sel_hi:[1,0,1]
	v_pk_mul_f32 v[48:49], v[44:45], v[194:195]
	v_pk_mul_f32 v[52:53], v[46:47], v[194:195]
	v_pk_mul_f32 v[54:55], v[40:41], v[194:195]
	v_pk_mul_f32 v[56:57], v[42:43], v[194:195]
	v_exp_f32_e32 v48, v48
	v_exp_f32_e32 v49, v49
	v_exp_f32_e32 v52, v52
	v_exp_f32_e32 v53, v53
	v_exp_f32_e32 v54, v54
	v_exp_f32_e32 v55, v55
	v_exp_f32_e32 v56, v56
	v_exp_f32_e32 v57, v57
	v_pk_add_f32 v[48:49], v[48:49], v[196:197]
	v_pk_add_f32 v[52:53], v[52:53], v[196:197]
	v_pk_add_f32 v[54:55], v[54:55], v[196:197]
	v_pk_add_f32 v[56:57], v[56:57], v[196:197]
	v_rcp_f32_e32 v48, v48
	v_rcp_f32_e32 v49, v49
	v_rcp_f32_e32 v52, v52
	v_rcp_f32_e32 v53, v53
	v_rcp_f32_e32 v54, v54
	v_rcp_f32_e32 v55, v55
	v_rcp_f32_e32 v56, v56
	v_rcp_f32_e32 v57, v57
	v_pk_mul_f32 v[44:45], v[44:45], v[48:49]
	v_pk_mul_f32 v[46:47], v[46:47], v[52:53]
	v_pk_mul_f32 v[40:41], v[40:41], v[54:55]
	v_pk_mul_f32 v[42:43], v[42:43], v[56:57]
	v_pk_mul_f32 v[36:37], v[36:37], v[44:45]
	v_pk_mul_f32 v[38:39], v[38:39], v[46:47]
	v_pk_mul_f32 v[40:41], v[32:33], v[40:41]
	v_pk_mul_f32 v[42:43], v[34:35], v[42:43]
	v_cvt_pk_f16_f32 v32, v36, v37
	v_cvt_pk_f16_f32 v33, v38, v39
	v_cvt_pk_f16_f32 v34, v40, v41
	v_cvt_pk_f16_f32 v35, v42, v43
	global_store_dwordx4 v[50:51], v[32:35], off
	s_nop 0
	s_nop 0
	v_add_u32_e32 v33, 0xa0, v160
	v_mad_i64_i32 v[34:35], s[24:25], v33, s57, v[162:163]
	v_lshl_add_u64 v[34:35], v[34:35], 0, v[166:167]
	v_fmamk_f32 v32, v246, 0x3a800000, v175
	v_rsq_f32_e32 v32, v32
	s_nop 0
	v_pk_fma_f32 v[28:29], v[28:29], v[32:33], v[112:113] op_sel_hi:[1,0,1]
	v_pk_fma_f32 v[30:31], v[30:31], v[32:33], v[114:115] op_sel_hi:[1,0,1]
	v_pk_fma_f32 v[24:25], v[24:25], v[32:33], v[104:105] op_sel_hi:[1,0,1]
	v_pk_fma_f32 v[26:27], v[26:27], v[32:33], v[106:107] op_sel_hi:[1,0,1]
	v_pk_fma_f32 v[20:21], v[20:21], v[32:33], v[116:117] op_sel_hi:[1,0,1]
	v_pk_fma_f32 v[22:23], v[22:23], v[32:33], v[118:119] op_sel_hi:[1,0,1]
	v_pk_fma_f32 v[16:17], v[16:17], v[32:33], v[108:109] op_sel_hi:[1,0,1]
	v_pk_fma_f32 v[18:19], v[18:19], v[32:33], v[110:111] op_sel_hi:[1,0,1]
	v_pk_mul_f32 v[32:33], v[28:29], v[194:195]
	v_pk_mul_f32 v[36:37], v[30:31], v[194:195]
	v_pk_mul_f32 v[38:39], v[24:25], v[194:195]
	v_pk_mul_f32 v[40:41], v[26:27], v[194:195]
	v_exp_f32_e32 v32, v32
	v_exp_f32_e32 v33, v33
	v_exp_f32_e32 v36, v36
	v_exp_f32_e32 v37, v37
	v_exp_f32_e32 v38, v38
	v_exp_f32_e32 v39, v39
	v_exp_f32_e32 v40, v40
	v_exp_f32_e32 v41, v41
	v_pk_add_f32 v[32:33], v[32:33], v[196:197]
	v_pk_add_f32 v[36:37], v[36:37], v[196:197]
	v_pk_add_f32 v[38:39], v[38:39], v[196:197]
	v_pk_add_f32 v[40:41], v[40:41], v[196:197]
	v_rcp_f32_e32 v32, v32
	v_rcp_f32_e32 v33, v33
	v_rcp_f32_e32 v36, v36
	v_rcp_f32_e32 v37, v37
	v_rcp_f32_e32 v38, v38
	v_rcp_f32_e32 v39, v39
	v_rcp_f32_e32 v40, v40
	v_rcp_f32_e32 v41, v41
	v_pk_mul_f32 v[28:29], v[28:29], v[32:33]
	v_pk_mul_f32 v[30:31], v[30:31], v[36:37]
	v_pk_mul_f32 v[24:25], v[24:25], v[38:39]
	v_pk_mul_f32 v[26:27], v[26:27], v[40:41]
	v_pk_mul_f32 v[20:21], v[20:21], v[28:29]
	v_pk_mul_f32 v[22:23], v[22:23], v[30:31]
	v_pk_mul_f32 v[24:25], v[16:17], v[24:25]
	v_pk_mul_f32 v[26:27], v[18:19], v[26:27]
	v_cvt_pk_f16_f32 v16, v20, v21
	v_cvt_pk_f16_f32 v17, v22, v23
	v_cvt_pk_f16_f32 v18, v24, v25
	v_cvt_pk_f16_f32 v19, v26, v27
	global_store_dwordx4 v[34:35], v[16:19], off
	s_nop 0
	s_nop 0
	v_add_u32_e32 v17, 0xb0, v160
	v_mad_i64_i32 v[18:19], s[24:25], v17, s57, v[162:163]
	v_lshl_add_u64 v[18:19], v[18:19], 0, v[166:167]
	v_fmamk_f32 v16, v247, 0x3a800000, v175
	v_rsq_f32_e32 v16, v16
	s_nop 0
	v_pk_fma_f32 v[12:13], v[12:13], v[16:17], v[112:113] op_sel_hi:[1,0,1]
	v_pk_fma_f32 v[14:15], v[14:15], v[16:17], v[114:115] op_sel_hi:[1,0,1]
	v_pk_fma_f32 v[8:9], v[8:9], v[16:17], v[104:105] op_sel_hi:[1,0,1]
	v_pk_fma_f32 v[10:11], v[10:11], v[16:17], v[106:107] op_sel_hi:[1,0,1]
	v_pk_fma_f32 v[4:5], v[4:5], v[16:17], v[116:117] op_sel_hi:[1,0,1]
	v_pk_fma_f32 v[6:7], v[6:7], v[16:17], v[118:119] op_sel_hi:[1,0,1]
	v_pk_fma_f32 v[0:1], v[0:1], v[16:17], v[108:109] op_sel_hi:[1,0,1]
	v_pk_fma_f32 v[2:3], v[2:3], v[16:17], v[110:111] op_sel_hi:[1,0,1]
	v_pk_mul_f32 v[16:17], v[12:13], v[194:195]
	v_pk_mul_f32 v[20:21], v[14:15], v[194:195]
	v_pk_mul_f32 v[22:23], v[8:9], v[194:195]
	v_pk_mul_f32 v[24:25], v[10:11], v[194:195]
	v_exp_f32_e32 v16, v16
	v_exp_f32_e32 v17, v17
	v_exp_f32_e32 v20, v20
	v_exp_f32_e32 v21, v21
	v_exp_f32_e32 v22, v22
	v_exp_f32_e32 v23, v23
	v_exp_f32_e32 v24, v24
	v_exp_f32_e32 v25, v25
	v_pk_add_f32 v[16:17], v[16:17], v[196:197]
	v_pk_add_f32 v[20:21], v[20:21], v[196:197]
	v_pk_add_f32 v[22:23], v[22:23], v[196:197]
	v_pk_add_f32 v[24:25], v[24:25], v[196:197]
	v_rcp_f32_e32 v16, v16
	v_rcp_f32_e32 v17, v17
	v_rcp_f32_e32 v20, v20
	v_rcp_f32_e32 v21, v21
	v_rcp_f32_e32 v22, v22
	v_rcp_f32_e32 v23, v23
	v_rcp_f32_e32 v24, v24
	v_rcp_f32_e32 v25, v25
	v_pk_mul_f32 v[12:13], v[12:13], v[16:17]
	v_pk_mul_f32 v[14:15], v[14:15], v[20:21]
	v_pk_mul_f32 v[8:9], v[8:9], v[22:23]
	v_pk_mul_f32 v[10:11], v[10:11], v[24:25]
	v_pk_mul_f32 v[4:5], v[4:5], v[12:13]
	v_pk_mul_f32 v[6:7], v[6:7], v[14:15]
	v_pk_mul_f32 v[8:9], v[0:1], v[8:9]
	v_pk_mul_f32 v[10:11], v[2:3], v[10:11]
	v_cvt_pk_f16_f32 v0, v4, v5
	v_cvt_pk_f16_f32 v1, v6, v7
	v_cvt_pk_f16_f32 v2, v8, v9
	v_cvt_pk_f16_f32 v3, v10, v11
	global_store_dwordx4 v[18:19], v[0:3], off
	s_cbranch_vccnz .LBB0_1581
	s_andn2_b64 vcc, exec, s[4:5]
	s_cbranch_vccnz .LBB0_1580
	s_barrier
	s_branch .LBB0_1580
